# mixer1 prompt units: eight gate loads hoisted ahead of the gate-multiply chain (in-order waits)
# speedup vs baseline: 1.0126x; 1.0008x over previous
; __device__ __forceinline__ unsigned pk2(float lo, float hi) { return pg8::cvt_pk_bf16(lo, hi); }
; __device__ __forceinline__ void phase_mixer1(const Params& p, LAS unsigned char* lds) {
;     ...
;                 const float bs = sgb[g * 128 + t];
; #pragma unroll
;                 for (int n = 0; n < 8; ++n) {
;                     const int col = g * 128 + n * 16 + 4 * fq; const v2u uw = *(const v2u*)(Z + (row0 + t) * NZ1 + 512 + col);
;                     const float u0 = __uint_as_float(uw.x << 16), u1 = __uint_as_float(uw.x & 0xffff0000u), u2 = __uint_as_float(uw.y << 16), u3 = __uint_as_float(uw.y & 0xffff0000u);
;                     v2u o; o.x = pk2(u0 * (acc[n][0] + bs), u1 * (acc[n][1] + bs)); o.y = pk2(u2 * (acc[n][2] + bs), u3 * (acc[n][3] + bs));
;                     *(v2u*)(Y + (row0 + t) * D + 512 + col) = o;
;                 }
.LBB0_881:
	s_lshl_b32 s6, s28, 7
	s_mov_b32 s17, s89
	s_mov_b32 s16, s88
	v_add_u32_e32 v24, s6, v96
	v_readlane_b32 s80, v254, 5
	v_ashrrev_i32_e32 v25, 31, v24
	v_readlane_b32 s84, v254, 9
	v_readlane_b32 s85, v254, 10
	v_mov_b64_e32 v[26:27], s[34:35]
	v_or_b32_e32 v30, s6, v144
	v_lshl_add_u64 v[24:25], v[24:25], 2, s[84:85]
	global_load_dword v32, v[24:25], off
	v_lshl_add_u64 v[24:25], s[0:1], 0, v[96:97]
	v_mad_u64_u32 v[26:27], s[0:1], v24, s65, v[26:27]
	v_mov_b32_e32 v28, v27
	v_mad_u64_u32 v[28:29], s[0:1], v25, s65, v[28:29]
	v_mov_b32_e32 v27, v28
	v_lshlrev_b32_e32 v78, 1, v30
	v_lshl_add_u64 v[26:27], v[26:27], 0, v[78:79]
	global_load_dwordx2 v[28:29], v[26:27], off offset:1024
	global_load_dwordx2 v[226:227], v[26:27], off offset:1056
	global_load_dwordx2 v[228:229], v[26:27], off offset:1088
	global_load_dwordx2 v[230:231], v[26:27], off offset:1120
	global_load_dwordx2 v[232:233], v[26:27], off offset:1152
	global_load_dwordx2 v[234:235], v[26:27], off offset:1184
	global_load_dwordx2 v[236:237], v[26:27], off offset:1216
	global_load_dwordx2 v[240:241], v[26:27], off offset:1248
	v_lshlrev_b64 v[24:25], 11, v[24:25]
	v_lshl_add_u64 v[24:25], s[36:37], 0, v[24:25]
	v_lshl_add_u64 v[24:25], v[24:25], 0, v[78:79]
	s_add_i32 s40, s9, s8
	v_or_b32_e32 v140, s40, v145
	s_mul_hi_i32 s53, s50, 0x600000
	s_cmp_lt_i32 s28, 2
	s_mul_i32 s52, s50, 0x600000
	v_readlane_b32 s81, v254, 6
	v_readlane_b32 s82, v254, 7
	v_readlane_b32 s83, v254, 8
	v_readlane_b32 s86, v254, 11
	v_readlane_b32 s87, v254, 12
	v_readlane_b32 s88, v254, 13
	v_readlane_b32 s89, v254, 14
	v_readlane_b32 s90, v254, 15
	v_readlane_b32 s91, v254, 16
	v_readlane_b32 s92, v254, 17
	v_readlane_b32 s93, v254, 18
	v_readlane_b32 s94, v254, 19
	v_readlane_b32 s95, v254, 20
	s_waitcnt vmcnt(8)
	v_add_f32_e32 v30, v44, v32
	v_add_f32_e32 v31, v45, v32
	v_add_f32_e32 v33, v46, v32
	v_add_f32_e32 v34, v47, v32
	v_add_f32_e32 v20, v20, v32
	v_add_f32_e32 v21, v21, v32
	v_add_f32_e32 v22, v22, v32
	v_add_f32_e32 v23, v23, v32
	v_add_f32_e32 v16, v16, v32
	v_add_f32_e32 v17, v17, v32
	s_waitcnt vmcnt(7)
	v_lshlrev_b32_e32 v35, 16, v28
	v_and_b32_e32 v28, 0xffff0000, v28
	v_lshlrev_b32_e32 v36, 16, v29
	v_and_b32_e32 v29, 0xffff0000, v29
	v_mul_f32_e32 v30, v30, v35
	v_mul_f32_e32 v28, v31, v28
	v_mul_f32_e32 v31, v33, v36
	v_mul_f32_e32 v29, v34, v29
	v_cvt_pk_bf16_f32 v28, v30, v28
	v_cvt_pk_bf16_f32 v29, v31, v29
	v_add_f32_e32 v33, v40, v32
	v_add_f32_e32 v34, v41, v32
	v_add_f32_e32 v35, v42, v32
	v_add_f32_e32 v36, v43, v32
	global_store_dwordx2 v[24:25], v[28:29], off offset:1024
	v_add_f32_e32 v18, v18, v32
	v_add_f32_e32 v19, v19, v32
	v_add_f32_e32 v12, v12, v32
	v_add_f32_e32 v13, v13, v32
	v_add_f32_e32 v14, v14, v32
	v_add_f32_e32 v15, v15, v32
	v_add_f32_e32 v8, v8, v32
	v_add_f32_e32 v9, v9, v32
	v_add_f32_e32 v10, v10, v32
	v_add_f32_e32 v11, v11, v32
	v_add_f32_e32 v4, v4, v32
	v_add_f32_e32 v5, v5, v32
	v_add_f32_e32 v6, v6, v32
	v_add_f32_e32 v7, v7, v32
	v_add_f32_e32 v0, v32, v0
	v_add_f32_e32 v1, v32, v1
	v_add_f32_e32 v2, v32, v2
	v_add_f32_e32 v3, v32, v3
	s_waitcnt vmcnt(7)
	v_mov_b32_e32 v30, v226
	v_mov_b32_e32 v31, v227
	v_lshlrev_b32_e32 v28, 16, v30
	v_and_b32_e32 v29, 0xffff0000, v30
	v_lshlrev_b32_e32 v30, 16, v31
	v_and_b32_e32 v31, 0xffff0000, v31
	v_mul_f32_e32 v28, v33, v28
	v_mul_f32_e32 v29, v34, v29
	v_mul_f32_e32 v30, v35, v30
	v_mul_f32_e32 v31, v36, v31
	v_cvt_pk_bf16_f32 v28, v28, v29
	v_cvt_pk_bf16_f32 v29, v30, v31
	s_nop 0
	global_store_dwordx2 v[24:25], v[28:29], off offset:1056
	s_waitcnt vmcnt(7)
	v_mov_b32_e32 v30, v228
	v_mov_b32_e32 v31, v229
	v_lshlrev_b32_e32 v28, 16, v30
	v_and_b32_e32 v29, 0xffff0000, v30
	v_lshlrev_b32_e32 v30, 16, v31
	v_and_b32_e32 v31, 0xffff0000, v31
	v_mul_f32_e32 v20, v20, v28
	v_mul_f32_e32 v21, v21, v29
	v_mul_f32_e32 v22, v22, v30
	v_mul_f32_e32 v23, v23, v31
	v_cvt_pk_bf16_f32 v20, v20, v21
	v_cvt_pk_bf16_f32 v21, v22, v23
	s_nop 0
	global_store_dwordx2 v[24:25], v[20:21], off offset:1088
	s_waitcnt vmcnt(7)
	v_mov_b32_e32 v22, v230
	v_mov_b32_e32 v23, v231
	v_lshlrev_b32_e32 v20, 16, v22
	v_and_b32_e32 v21, 0xffff0000, v22
	v_lshlrev_b32_e32 v22, 16, v23
	v_and_b32_e32 v23, 0xffff0000, v23
	v_mul_f32_e32 v16, v16, v20
	v_mul_f32_e32 v17, v17, v21
	v_mul_f32_e32 v18, v18, v22
	v_mul_f32_e32 v19, v19, v23
	v_cvt_pk_bf16_f32 v16, v16, v17
	v_cvt_pk_bf16_f32 v17, v18, v19
	s_nop 0
	global_store_dwordx2 v[24:25], v[16:17], off offset:1120
	s_waitcnt vmcnt(7)
	v_mov_b32_e32 v18, v232
	v_mov_b32_e32 v19, v233
	v_lshlrev_b32_e32 v16, 16, v18
	v_and_b32_e32 v17, 0xffff0000, v18
	v_lshlrev_b32_e32 v18, 16, v19
	v_and_b32_e32 v19, 0xffff0000, v19
	v_mul_f32_e32 v12, v12, v16
	v_mul_f32_e32 v13, v13, v17
	v_mul_f32_e32 v14, v14, v18
	v_mul_f32_e32 v15, v15, v19
	v_cvt_pk_bf16_f32 v12, v12, v13
	v_cvt_pk_bf16_f32 v13, v14, v15
	s_nop 0
	global_store_dwordx2 v[24:25], v[12:13], off offset:1152
	s_waitcnt vmcnt(7)
	v_mov_b32_e32 v14, v234
	v_mov_b32_e32 v15, v235
	v_lshlrev_b32_e32 v12, 16, v14
	v_and_b32_e32 v13, 0xffff0000, v14
	v_lshlrev_b32_e32 v14, 16, v15
	v_and_b32_e32 v15, 0xffff0000, v15
	v_mul_f32_e32 v8, v8, v12
	v_mul_f32_e32 v9, v9, v13
	v_mul_f32_e32 v10, v10, v14
	v_mul_f32_e32 v11, v11, v15
	v_cvt_pk_bf16_f32 v8, v8, v9
	v_cvt_pk_bf16_f32 v9, v10, v11
	s_nop 0
	global_store_dwordx2 v[24:25], v[8:9], off offset:1184
	s_waitcnt vmcnt(7)
	v_mov_b32_e32 v10, v236
	v_mov_b32_e32 v11, v237
	v_lshlrev_b32_e32 v8, 16, v10
	v_and_b32_e32 v9, 0xffff0000, v10
	v_lshlrev_b32_e32 v10, 16, v11
	v_and_b32_e32 v11, 0xffff0000, v11
	v_mul_f32_e32 v4, v4, v8
	v_mul_f32_e32 v5, v5, v9
	v_mul_f32_e32 v6, v6, v10
	v_mul_f32_e32 v7, v7, v11
	v_cvt_pk_bf16_f32 v4, v4, v5
	v_cvt_pk_bf16_f32 v5, v6, v7
	s_nop 0
	global_store_dwordx2 v[24:25], v[4:5], off offset:1216
	s_waitcnt vmcnt(7)
	v_mov_b32_e32 v6, v240
	v_mov_b32_e32 v7, v241
	v_lshlrev_b32_e32 v4, 16, v6
	v_and_b32_e32 v5, 0xffff0000, v6
	v_lshlrev_b32_e32 v6, 16, v7
	v_and_b32_e32 v7, 0xffff0000, v7
	v_mul_f32_e32 v0, v0, v4
	v_mul_f32_e32 v1, v1, v5
	v_mul_f32_e32 v2, v2, v6
	v_mul_f32_e32 v3, v3, v7
	v_cvt_pk_bf16_f32 v0, v0, v1
	v_cvt_pk_bf16_f32 v1, v2, v3
	global_store_dwordx2 v[24:25], v[0:1], off offset:1248
	s_cbranch_scc1 .LBB0_915
	s_cmp_gt_i32 s28, 2
	s_mov_b32 s88, s16
	s_mov_b32 s89, s17
	s_cbranch_scc0 .LBB0_916
	v_lshl_add_u64 v[4:5], v[98:99], 0, s[52:53]
	v_cmp_lt_i32_e32 vcc, 14, v140
	v_mov_b32_e32 v0, 0
	v_mov_b32_e32 v8, 0
	v_mov_b32_e32 v9, 0
	v_mov_b32_e32 v10, 0
	v_mov_b32_e32 v11, 0
	s_and_saveexec_b64 s[0:1], vcc
	s_cbranch_execz .LBB0_885
	v_add_u32_e32 v1, -15, v140
	v_mad_u64_u32 v[2:3], s[6:7], v1, s65, v[4:5]
	global_load_dwordx4 v[8:11], v[2:3], off
